# LN+router phase: pipelined router-weight LDS reads, reduce-scatter and remaining shuffles via permlane/DPP
# speedup vs baseline: 1.0700x; 1.0120x over previous
; __device__ __forceinline__ int fresh_tid() { int t = threadIdx.x; asm volatile("" : "+v"(t)); return t; }
; #define PG8_STAGE_A(bufoff, gbase, h) do { if constexpr (GATHER) PG8_STAGE(bufoff, gbase, go[h][0], go[h][1]); else PG8_STAGE(bufoff, (gbase) + (h) * hstep, voffA[0], voffA[1]); } while (0)
; #define PG8_WAIT_V(n) asm volatile("s_waitcnt vmcnt(" #n ")" ::: "memory")
; #define PG8_BAR __builtin_amdgcn_s_barrier()
; #define PG8_GOFFS(u) do { _Pragma("unroll") for (int h = 0; h < 2; ++h) _Pragma("unroll") for (int i = 0; i < 2; ++i) \
;         go[h][i] = (unsigned)(S.idx[(u).pm * BM + h * HALF + R0 + 64 * i] * K + C0) * 2u; } while (0)
; template <bool GATHER, class Epi>
; __device__ __forceinline__ void gemm_phase(LAS unsigned char* lds, const Sched& S, const Epi& E) {
;     const int tid = fresh_tid(), wid = __builtin_amdgcn_readfirstlane(tid >> 6), lane = tid & 63, wr = wid >> 2, wc = wid & 3, fr = lane & 15, fq = lane >> 4;
;     const int K = S.K, nt = K / BK;
;     int R0, C0; unsigned voffA[2], voffB[2];
;     { int R, C; stage_rc(tid * 16, R, C); R0 = R; C0 = C; }
; #pragma unroll
;     for (int i = 0; i < 2; ++i) { int R, C; stage_rc(tid * 16 + i * 8192, R, C); const int Rb = Epi::PERM ? ((R & ~31) + perm32(R & 31)) : R; voffA[i] = (unsigned)(R * K + C) * 2u; voffB[i] = (unsigned)(Rb * K + C) * 2u; }
;     const size_t kstep = (size_t)(BK * 2);
;     const size_t hstep = (size_t)HALF * K * 2;
;     const size_t tstep = 2 * hstep;
;     const size_t b1off = S.b1off;
;     const unsigned ldsw = (unsigned)wid * 1024u;
;     const int aoff = lds_byte(wr * 64 + fr, fq * 8), boff = lds_byte(wc * 32 + fr, fq * 8);
;     ...
;     const char* cA = GATHER ? S.A : S.A + (size_t)cur.pm * tstep + (size_t)cur.br * S.abr; const char* cB = S.bptr(cur);
;     if constexpr (GATHER) PG8_GOFFS(cur);
;     PG8_STAGE(PG8_SB(0, 0), cB, voffB[0], voffB[1]); PG8_STAGE_A(PG8_SA(0, 0), cA, 0); PG8_STAGE(PG8_SB(0, 1), cB + b1off, voffB[0], voffB[1]); PG8_STAGE_A(PG8_SA(0, 1), cA, 1);
;     if (wr == 1) PG8_BAR;
;     PG8_WAIT_V(4); PG8_BAR;
;     PG8_STAGE(PG8_SB(1, 0), cB + kstep, voffB[0], voffB[1]); PG8_STAGE_A(PG8_SA(1, 0), cA + kstep, 0); PG8_STAGE(PG8_SB(1, 1), cB + b1off + kstep, voffB[0], voffB[1]);
.LBB0_112:
	s_andn2_b64 vcc, exec, s[4:5]
	s_cbranch_vccnz .LBB0_131
	v_readlane_b32 s4, v252, 10
	s_waitcnt vmcnt(0)
	v_mov_b32_e32 v0, v213
	v_readlane_b32 s5, v252, 11
	s_andn2_b64 vcc, exec, s[4:5]
	v_readfirstlane_b32 s18, v0
	s_cbranch_vccnz .LBB0_131
	v_bfe_i32 v3, v0, 27, 1
	v_lshlrev_b32_e32 v1, 4, v0
	v_lshrrev_b32_e32 v3, 22, v3
	v_add_u32_e32 v3, v1, v3
	v_and_b32_e32 v3, 0xfffffc00, v3
	v_sub_u32_e32 v3, v1, v3
	v_lshrrev_b32_e32 v4, 4, v3
	v_bitop3_b32 v4, v4, v3, 32 bitop3:0x6c
	v_ashrrev_i32_e32 v3, 31, v3
	v_lshrrev_b32_e32 v3, 26, v3
	v_ashrrev_i32_e32 v2, 31, v0
	v_add_u32_e32 v3, v4, v3
	v_lshrrev_b32_e32 v2, 26, v2
	v_ashrrev_i32_e32 v3, 6, v3
	v_add_u32_e32 v2, v0, v2
	v_mul_i32_i24_e32 v6, 64, v3
	v_ashrrev_i32_e32 v2, 6, v2
	v_sub_u32_e32 v4, v4, v6
	s_ashr_i32 s27, s26, 31
	v_lshlrev_b32_e32 v5, 3, v2
	v_lshlrev_b32_e32 v2, 5, v2
	v_ashrrev_i16_sdwa v4, v215, sext(v4) dst_sel:DWORD dst_unused:UNUSED_PAD src0_sel:DWORD src1_sel:BYTE_0
	s_lshl_b64 s[4:5], s[26:27], 26
	v_bfe_i32 v4, v4, 0, 16
	v_and_b32_e32 v5, -16, v5
	v_and_b32_e32 v2, 32, v2
	v_add_u32_e32 v1, 0x2000, v1
	s_add_u32 s19, s69, s4
	v_add_u32_e32 v222, v3, v5
	v_add_lshl_u32 v223, v2, v4, 1
	v_ashrrev_i32_e32 v2, 31, v1
	s_addc_u32 s20, s84, s5
	v_lshlrev_b32_e32 v5, 1, v222
	v_lshrrev_b32_e32 v6, 2, v222
	v_and_b32_e32 v3, 3, v3
	s_mov_b32 s5, 0x1fffe0
	v_lshrrev_b32_e32 v2, 22, v2
	v_and_b32_e32 v5, 24, v5
	v_and_b32_e32 v6, 4, v6
	v_and_or_b32 v3, v222, s5, v3
	v_add_u32_e32 v2, v1, v2
	v_or3_b32 v3, v3, v6, v5
	v_ashrrev_i32_e32 v2, 10, v2
	v_lshl_add_u32 v224, v3, 11, v223
	v_mul_i32_i24_e32 v3, 0x400, v2
	v_sub_u32_e32 v1, v1, v3
	v_lshrrev_b32_e32 v3, 4, v1
	v_bitop3_b32 v1, v3, v1, 32 bitop3:0x6c
	v_ashrrev_i32_e32 v4, 31, v1
	v_lshrrev_b32_e32 v4, 26, v4
	v_lshlrev_b32_e32 v3, 3, v2
	v_add_u32_e32 v4, v1, v4
	v_and_b32_e32 v3, -16, v3
	v_ashrrev_i32_e32 v5, 6, v4
	v_add_u32_e32 v3, v5, v3
	v_and_b32_e32 v4, 0xc0, v4
	v_and_b32_e32 v5, 3, v5
	v_sub_u32_e32 v1, v1, v4
	v_lshlrev_b32_e32 v4, 1, v3
	v_lshrrev_b32_e32 v6, 2, v3
	v_and_or_b32 v3, v3, s5, v5
	s_ashr_i32 s5, s18, 6
	s_ashr_i32 s4, s18, 8
	s_lshl_b32 s21, s5, 10
	v_readlane_b32 s6, v253, 53
	v_readlane_b32 s7, v253, 54
	s_add_u32 s6, s19, s6
	v_lshlrev_b32_e32 v2, 5, v2
	v_ashrrev_i16_sdwa v1, v215, sext(v1) dst_sel:DWORD dst_unused:UNUSED_PAD src0_sel:DWORD src1_sel:BYTE_0
	s_addc_u32 s7, s20, s7
	v_readlane_b32 s8, v253, 56
	v_and_b32_e32 v2, 32, v2
	v_bfe_i32 v1, v1, 0, 16
	v_and_b32_e32 v4, 24, v4
	v_and_b32_e32 v6, 4, v6
	v_readlane_b32 s9, v253, 57
	s_add_u32 s12, s6, s8
	v_readlane_b32 s6, v253, 59
	v_or3_b32 v3, v3, v6, v4
	v_add_lshl_u32 v1, v2, v1, 1
	s_addc_u32 s13, s7, s9
	v_add_u32_e32 v2, s6, v222
	v_readlane_b32 s6, v252, 26
	v_lshl_add_u32 v225, v3, 11, v1
	v_ashrrev_i32_e32 v3, 31, v2
	v_readlane_b32 s7, v252, 27
	s_add_i32 s22, s21, 0
	s_add_i32 s23, s22, 0x10000
	v_lshl_add_u64 v[4:5], v[2:3], 2, s[6:7]
	global_load_dword v198, v[4:5], off
	global_load_dword v199, v[4:5], off offset:256
	global_load_dword v200, v[4:5], off offset:512
	global_load_dword v201, v[4:5], off offset:768
	s_mov_b32 m0, s23
	s_add_i32 s24, s22, 0x12000
	s_add_i32 s25, s22, 0x2000
	s_mov_b32 s54, s26
	s_add_u32 s6, s12, 0x8000000
	s_addc_u32 s7, s13, 0
	s_add_i32 s26, s22, 0x4000
	s_add_i32 s27, s22, 0x6000
	v_mov_b32_e32 v2, v224
	s_waitcnt vmcnt(0)
	v_lshl_add_u32 v226, v198, 11, v223
	v_lshl_add_u32 v227, v199, 11, v223
	v_lshl_add_u32 v228, v200, 11, v223
	v_lshl_add_u32 v229, v201, 11, v223
	v_mov_b32_e32 v1, v225
	s_nop 0
	global_load_lds_dwordx4 v2, s[12:13]
	s_mov_b32 m0, s24
	v_mov_b32_e32 v2, v226
	global_load_lds_dwordx4 v1, s[12:13]
	v_mov_b32_e32 v1, v227
	s_mov_b32 m0, s22
	s_nop 0
	global_load_lds_dwordx4 v2, s[66:67]
	s_mov_b32 m0, s25
	v_mov_b32_e32 v2, v224
	global_load_lds_dwordx4 v1, s[66:67]
	v_mov_b32_e32 v1, v225
	s_add_i32 m0, s22, 0x14000
	s_nop 0
	global_load_lds_dwordx4 v2, s[6:7]
	s_add_i32 m0, s22, 0x16000
	v_mov_b32_e32 v2, v228
	global_load_lds_dwordx4 v1, s[6:7]
	v_mov_b32_e32 v1, v229
	s_mov_b32 m0, s26
	s_cmp_lg_u32 s4, 1
	global_load_lds_dwordx4 v2, s[66:67]
	s_mov_b32 m0, s27
	s_nop 0
	global_load_lds_dwordx4 v1, s[66:67]
	s_cbranch_scc1 .LBB0_116
	s_barrier

; #define LAS __attribute__((address_space(3)))
; __device__ __forceinline__ unsigned cvt_pk_bf16(float lo, float hi) { unsigned r; asm("v_cvt_pk_bf16_f32 %0, %1, %2" : "=v"(r) : "v"(lo), "v"(hi)); return r; }
; __device__ __forceinline__ float bf_lo(unsigned w) { return __uint_as_float(w << 16); }
; __device__ __forceinline__ float bf_hi(unsigned w) { return __uint_as_float(w & 0xffff0000u); }
; __device__ void phase_ln1_router(const Params& p, int l, LAS unsigned char* lds) {
;     ...
;         f32x4 v[4]; float s = 0.f;
; #pragma unroll
;         for (int j = 0; j < 4; ++j) { const u32x2 w = raw[j]; v[j] = (f32x4){bf_lo(w.x), bf_hi(w.x), bf_lo(w.y), bf_hi(w.y)}; s += (v[j][0] + v[j][1]) + (v[j][2] + v[j][3]); }
;         if (row + rstride < SEQ) {
; #pragma unroll
;             for (int j = 0; j < 4; ++j) raw[j] = *(const u32x2*)(XP + (size_t)(row + rstride) * DM + lane * 4 + 256 * j); }
;         const float mean = wave_sum(s) * (1.0f / 1024.0f); float q = 0.f;
; #pragma unroll
;         for (int j = 0; j < 4; ++j) { v[j] = v[j] - mean; q += (v[j][0] * v[j][0] + v[j][1] * v[j][1]) + (v[j][2] * v[j][2] + v[j][3] * v[j][3]); }
;         const float rstd = rsqrtf(wave_sum(q) * (1.0f / 1024.0f) + 1e-5f);
; #pragma unroll
;         for (int j = 0; j < 4; ++j) { v[j] = v[j] * rstd * gv[j] + bv[j];
;             u32x2 w; w.x = cvt_pk_bf16(v[j][0], v[j][1]); w.y = cvt_pk_bf16(v[j][2], v[j][3]); *(u32x2*)(XB + (size_t)row * DM + lane * 4 + 256 * j) = w; }
;         float a16[16];
; #pragma unroll
;         for (int e = 0; e < 16; ++e) { float a = 0.f;
; #pragma unroll
;             for (int j = 0; j < 4; ++j) { const f32x4 w = *(const LAS f32x4*)(rw_s + e * RWP + lane * 4 + 256 * j); a += v[j][0] * w[0] + v[j][1] * w[1] + v[j][2] * w[2] + v[j][3] * w[3]; }
.LBB0_316:
	s_or_b64 exec, exec, s[20:21]
	v_lshlrev_b32_e32 v56, 16, v54
	v_and_b32_e32 v57, 0xffff0000, v54
	v_lshlrev_b32_e32 v54, 16, v55
	v_and_b32_e32 v55, 0xffff0000, v55
	v_add_f32_e32 v33, v56, v57
	v_add_f32_e32 v58, v54, v55
	v_add_f32_e32 v33, v33, v58
	v_lshlrev_b32_e32 v58, 16, v52
	v_and_b32_e32 v59, 0xffff0000, v52
	v_lshlrev_b32_e32 v52, 16, v53
	v_and_b32_e32 v53, 0xffff0000, v53
	v_add_f32_e32 v60, v58, v59
	v_add_f32_e32 v61, v52, v53
	v_add_f32_e32 v33, 0, v33
	v_add_f32_e32 v60, v60, v61
	v_lshlrev_b32_e32 v72, 16, v50
	v_and_b32_e32 v73, 0xffff0000, v50
	v_lshlrev_b32_e32 v50, 16, v51
	v_and_b32_e32 v51, 0xffff0000, v51
	v_add_f32_e32 v33, v33, v60
	v_add_f32_e32 v60, v72, v73
	v_add_f32_e32 v61, v50, v51
	v_add_f32_e32 v60, v60, v61
	v_lshlrev_b32_e32 v74, 16, v48
	v_and_b32_e32 v75, 0xffff0000, v48
	v_lshlrev_b32_e32 v48, 16, v49
	v_and_b32_e32 v49, 0xffff0000, v49
	v_add_f32_e32 v33, v33, v60
	v_add_f32_e32 v60, v74, v75
	v_add_f32_e32 v61, v48, v49
	v_add_f32_e32 v60, v60, v61
	v_add_f32_e32 v33, v33, v60
	v_mov_b32_e32 v60, v33
	s_mov_b32 s20, 0x1a601000
	s_waitcnt lgkmcnt(0)
	s_nop 1
	v_permlane32_swap_b32_e32 v60, v33
	v_add_f32_e32 v33, v33, v60
	v_mov_b32_e32 v60, v33
	s_waitcnt lgkmcnt(0)
	s_nop 1
	v_permlane16_swap_b32_e32 v60, v33
	v_add_f32_e32 v33, v33, v60
	s_waitcnt lgkmcnt(0)
	s_nop 1
	v_add_f32_dpp v33, v33, v33 row_ror:8 row_mask:0xf bank_mask:0xf
	s_waitcnt lgkmcnt(0)
	s_nop 1
	v_add_f32_dpp v33, v33, v33 row_ror:4 row_mask:0xf bank_mask:0xf
	s_waitcnt lgkmcnt(0)
	s_nop 1
	v_add_f32_dpp v33, v33, v33 quad_perm:[2,3,0,1] row_mask:0xf bank_mask:0xf
	s_waitcnt lgkmcnt(0)
	s_nop 1
	v_add_f32_dpp v33, v33, v33 quad_perm:[1,0,3,2] row_mask:0xf bank_mask:0xf
	v_fmac_f32_e32 v57, 0xba800000, v33
	v_fmac_f32_e32 v56, 0xba800000, v33
	v_fmac_f32_e32 v55, 0xba800000, v33
	v_fmac_f32_e32 v54, 0xba800000, v33
	v_pk_mul_f32 v[60:61], v[54:55], v[54:55]
	v_pk_mul_f32 v[62:63], v[56:57], v[56:57]
	v_fmac_f32_e32 v59, 0xba800000, v33
	v_pk_mov_b32 v[76:77], v[62:63], v[60:61] op_sel:[1,0]
	v_mov_b32_e32 v63, v61
	v_pk_add_f32 v[60:61], v[76:77], v[62:63]
	v_fmac_f32_e32 v58, 0xba800000, v33
	v_fmac_f32_e32 v53, 0xba800000, v33
	v_fmac_f32_e32 v52, 0xba800000, v33
	v_pk_add_f32 v[60:61], v[60:61], v[60:61] op_sel_hi:[0,1]
	v_pk_mul_f32 v[62:63], v[52:53], v[52:53]
	v_pk_mul_f32 v[76:77], v[58:59], v[58:59]
	v_fmac_f32_e32 v72, 0xba800000, v33
	v_pk_mov_b32 v[78:79], v[76:77], v[62:63] op_sel:[1,0]
	v_mov_b32_e32 v77, v63
	v_fmac_f32_e32 v73, 0xba800000, v33
	v_fmac_f32_e32 v50, 0xba800000, v33
	v_mul_f32_e32 v60, v72, v72
	v_pk_add_f32 v[62:63], v[78:79], v[76:77]
	v_fmac_f32_e32 v51, 0xba800000, v33
	v_pk_fma_f32 v[76:77], v[72:73], v[72:73], v[60:61] op_sel_hi:[1,1,0]
	v_mul_f32_e32 v60, v50, v50
	v_pk_add_f32 v[62:63], v[62:63], v[62:63] op_sel_hi:[0,1]
	v_pk_fma_f32 v[78:79], v[50:51], v[50:51], v[60:61] op_sel_hi:[1,1,0]
	v_fmac_f32_e32 v49, 0xba800000, v33
	v_fmac_f32_e32 v48, 0xba800000, v33
	v_fmac_f32_e32 v75, 0xba800000, v33
	v_fmac_f32_e32 v74, 0xba800000, v33
	v_mul_f32_e32 v76, v74, v74
	v_mul_f32_e32 v78, v75, v75
	v_mul_f32_e32 v60, v48, v48
	v_mul_f32_e32 v62, v49, v49
	v_pk_add_f32 v[76:77], v[76:77], v[78:79]
	v_pk_add_f32 v[60:61], v[60:61], v[62:63]
	v_lshl_add_u64 v[78:79], s[86:87], 0, v[34:35]
	v_pk_add_f32 v[60:61], v[76:77], v[60:61]
	s_nop 0
	v_add_f32_e32 v33, v60, v61
	v_mov_b32_e32 v60, v33
	s_waitcnt lgkmcnt(0)
	s_nop 1
	v_permlane32_swap_b32_e32 v60, v33
	v_add_f32_e32 v33, v33, v60
	v_mov_b32_e32 v60, v33
	s_waitcnt lgkmcnt(0)
	s_nop 1
	v_permlane16_swap_b32_e32 v60, v33
	v_add_f32_e32 v33, v33, v60
	s_waitcnt lgkmcnt(0)
	s_nop 1
	v_add_f32_dpp v33, v33, v33 row_ror:8 row_mask:0xf bank_mask:0xf
	s_waitcnt lgkmcnt(0)
	s_nop 1
	v_add_f32_dpp v33, v33, v33 row_ror:4 row_mask:0xf bank_mask:0xf
	s_waitcnt lgkmcnt(0)
	s_nop 1
	v_add_f32_dpp v33, v33, v33 quad_perm:[2,3,0,1] row_mask:0xf bank_mask:0xf
	s_waitcnt lgkmcnt(0)
	s_nop 1
	v_add_f32_dpp v33, v33, v33 quad_perm:[1,0,3,2] row_mask:0xf bank_mask:0xf
	v_mov_b32_e32 v60, 0x3727c5ac
	v_fmamk_f32 v33, v33, 0x3a800000, v60
	v_cmp_gt_f32_e32 vcc, s1, v33
	v_mul_f32_e32 v60, 0x4b800000, v33
	s_nop 0
	v_cndmask_b32_e32 v33, v33, v60, vcc
	v_rsq_f32_e32 v33, v33
	s_nop 0
	v_mul_f32_e32 v60, 0x45800000, v33
	v_cndmask_b32_e32 v76, v33, v60, vcc
	v_pk_mul_f32 v[56:57], v[56:57], v[76:77] op_sel_hi:[1,0]
	v_pk_mul_f32 v[54:55], v[54:55], v[76:77] op_sel_hi:[1,0]
	v_add_co_u32_e32 v78, vcc, s20, v78
	v_pk_fma_f32 v[60:61], v[30:31], v[54:55], v[26:27]
	v_pk_fma_f32 v[62:63], v[28:29], v[56:57], v[24:25]
	v_cvt_pk_bf16_f32 v55, v60, v61
	v_addc_co_u32_e32 v79, vcc, 0, v79, vcc
	v_cvt_pk_bf16_f32 v54, v62, v63
	global_store_dwordx2 v[78:79], v[54:55], off
	v_pk_mul_f32 v[54:55], v[58:59], v[76:77] op_sel_hi:[1,0]
	v_pk_mul_f32 v[52:53], v[52:53], v[76:77] op_sel_hi:[1,0]
	v_pk_fma_f32 v[54:55], v[20:21], v[54:55], v[16:17]
	v_pk_fma_f32 v[52:53], v[22:23], v[52:53], v[18:19]
	v_cvt_pk_bf16_f32 v56, v54, v55
	v_pk_mul_f32 v[58:59], v[72:73], v[76:77] op_sel_hi:[1,0]
	v_cvt_pk_bf16_f32 v57, v52, v53
	v_pk_mul_f32 v[50:51], v[50:51], v[76:77] op_sel_hi:[1,0]
	global_store_dwordx2 v[78:79], v[56:57], off offset:512
	v_pk_fma_f32 v[56:57], v[14:15], v[50:51], v[10:11]
	v_pk_fma_f32 v[58:59], v[12:13], v[58:59], v[8:9]
	v_cvt_pk_bf16_f32 v51, v56, v57
	v_pk_mul_f32 v[48:49], v[48:49], v[76:77] op_sel_hi:[1,0]
	v_cvt_pk_bf16_f32 v50, v58, v59
	global_store_dwordx2 v[78:79], v[50:51], off offset:1024
	v_pk_mul_f32 v[50:51], v[74:75], v[76:77] op_sel_hi:[1,0]
	v_pk_fma_f32 v[48:49], v[6:7], v[48:49], v[2:3]
	v_pk_fma_f32 v[50:51], v[4:5], v[50:51], v[0:1]
	v_cvt_pk_bf16_f32 v73, v48, v49
	s_mov_b32 s20, 0x3fb8aa3b
	v_cvt_pk_bf16_f32 v72, v50, v51
	global_store_dwordx2 v[78:79], v[72:73], off offset:1536
	ds_read_b128 v[92:95], v70
	ds_read_b128 v[96:99], v70 offset:1024
	ds_read_b128 v[100:103], v70 offset:2048
	ds_read_b128 v[104:107], v70 offset:3072
	ds_read_b128 v[108:111], v70 offset:4112
	ds_read_b128 v[112:115], v70 offset:5136
	ds_read_b128 v[116:119], v70 offset:6160
	ds_read_b128 v[120:123], v70 offset:7184
	ds_read_b128 v[124:127], v70 offset:8224
	ds_read_b128 v[128:131], v70 offset:9248
	ds_read_b128 v[132:135], v70 offset:10272
	ds_read_b128 v[136:139], v70 offset:11296
	s_waitcnt lgkmcnt(11)
; #define LAS __attribute__((address_space(3)))
; __device__ void phase_ln1_router(const Params& p, int l, LAS unsigned char* lds) {
;     ...
;         float a16[16];
; #pragma unroll
;         for (int e = 0; e < 16; ++e) { float a = 0.f;
; #pragma unroll
;             for (int j = 0; j < 4; ++j) { const f32x4 w = *(const LAS f32x4*)(rw_s + e * RWP + lane * 4 + 256 * j); a += v[j][0] * w[0] + v[j][1] * w[1] + v[j][2] * w[2] + v[j][3] * w[3]; }
;             a16[e] = a; }
	v_mul_f32_e32 v152, v93, v63
	v_fmac_f32_e32 v152, v92, v62
	v_fmac_f32_e32 v152, v94, v60
	v_fmac_f32_e32 v152, v95, v61
	ds_read_b128 v[92:95], v70 offset:12336
	v_add_f32_e32 v33, 0, v152
	s_waitcnt lgkmcnt(11)
	v_mul_f32_e32 v152, v97, v55
	v_fmac_f32_e32 v152, v96, v54
	v_fmac_f32_e32 v152, v98, v52
	v_fmac_f32_e32 v152, v99, v53
	ds_read_b128 v[96:99], v70 offset:13360
	v_add_f32_e32 v33, v152, v33
	s_waitcnt lgkmcnt(11)
	v_mul_f32_e32 v152, v101, v59
	v_fmac_f32_e32 v152, v100, v58
	v_fmac_f32_e32 v152, v102, v56
	v_fmac_f32_e32 v152, v103, v57
	ds_read_b128 v[100:103], v70 offset:14384
	v_add_f32_e32 v33, v152, v33
	s_waitcnt lgkmcnt(11)
	v_mul_f32_e32 v152, v105, v51
	v_fmac_f32_e32 v152, v104, v50
	v_fmac_f32_e32 v152, v106, v48
	v_fmac_f32_e32 v152, v107, v49
	ds_read_b128 v[104:107], v70 offset:15408
	v_add_f32_e32 v33, v152, v33
	s_waitcnt lgkmcnt(11)
	v_mul_f32_e32 v152, v109, v63
	v_fmac_f32_e32 v152, v108, v62
	v_fmac_f32_e32 v152, v110, v60
	v_fmac_f32_e32 v152, v111, v61
	ds_read_b128 v[108:111], v70 offset:16448
	v_add_f32_e32 v71, 0, v152
	s_waitcnt lgkmcnt(11)
	v_mul_f32_e32 v152, v113, v55
	v_fmac_f32_e32 v152, v112, v54
	v_fmac_f32_e32 v152, v114, v52
	v_fmac_f32_e32 v152, v115, v53
	ds_read_b128 v[112:115], v70 offset:17472
	v_add_f32_e32 v71, v152, v71
	s_waitcnt lgkmcnt(11)
	v_mul_f32_e32 v152, v117, v59
	v_fmac_f32_e32 v152, v116, v58
	v_fmac_f32_e32 v152, v118, v56
	v_fmac_f32_e32 v152, v119, v57
	ds_read_b128 v[116:119], v70 offset:18496
	v_add_f32_e32 v71, v152, v71
	s_waitcnt lgkmcnt(11)
	v_mul_f32_e32 v152, v121, v51
	v_fmac_f32_e32 v152, v120, v50
	v_fmac_f32_e32 v152, v122, v48
	v_fmac_f32_e32 v152, v123, v49
	ds_read_b128 v[120:123], v70 offset:19520
	v_add_f32_e32 v71, v152, v71
	s_waitcnt lgkmcnt(11)
	v_mul_f32_e32 v152, v125, v63
	v_fmac_f32_e32 v152, v124, v62
	v_fmac_f32_e32 v152, v126, v60
	v_fmac_f32_e32 v152, v127, v61
	ds_read_b128 v[124:127], v70 offset:20560
	v_add_f32_e32 v72, 0, v152
	s_waitcnt lgkmcnt(11)
	v_mul_f32_e32 v152, v129, v55
	v_fmac_f32_e32 v152, v128, v54
	v_fmac_f32_e32 v152, v130, v52
	v_fmac_f32_e32 v152, v131, v53
	ds_read_b128 v[128:131], v70 offset:21584
	v_add_f32_e32 v72, v152, v72
	s_waitcnt lgkmcnt(11)
	v_mul_f32_e32 v152, v133, v59
	v_fmac_f32_e32 v152, v132, v58
	v_fmac_f32_e32 v152, v134, v56
	v_fmac_f32_e32 v152, v135, v57
	ds_read_b128 v[132:135], v70 offset:22608
	v_add_f32_e32 v72, v152, v72
	s_waitcnt lgkmcnt(11)
	v_mul_f32_e32 v152, v137, v51
	v_fmac_f32_e32 v152, v136, v50
	v_fmac_f32_e32 v152, v138, v48
	v_fmac_f32_e32 v152, v139, v49
	ds_read_b128 v[136:139], v70 offset:23632
	v_add_f32_e32 v72, v152, v72
	s_waitcnt lgkmcnt(11)
	v_mul_f32_e32 v152, v93, v63
	v_fmac_f32_e32 v152, v92, v62
	v_fmac_f32_e32 v152, v94, v60
	v_fmac_f32_e32 v152, v95, v61
	ds_read_b128 v[92:95], v70 offset:24672
	v_add_f32_e32 v73, 0, v152
	s_waitcnt lgkmcnt(11)
	v_mul_f32_e32 v152, v97, v55
	v_fmac_f32_e32 v152, v96, v54
	v_fmac_f32_e32 v152, v98, v52
	v_fmac_f32_e32 v152, v99, v53
	ds_read_b128 v[96:99], v70 offset:25696
	v_add_f32_e32 v73, v152, v73
	s_waitcnt lgkmcnt(11)
	v_mul_f32_e32 v152, v101, v59
	v_fmac_f32_e32 v152, v100, v58
	v_fmac_f32_e32 v152, v102, v56
	v_fmac_f32_e32 v152, v103, v57
	ds_read_b128 v[100:103], v70 offset:26720
	v_add_f32_e32 v73, v152, v73
	s_waitcnt lgkmcnt(11)
	v_mul_f32_e32 v152, v105, v51
	v_fmac_f32_e32 v152, v104, v50
	v_fmac_f32_e32 v152, v106, v48
	v_fmac_f32_e32 v152, v107, v49
	ds_read_b128 v[104:107], v70 offset:27744
	v_add_f32_e32 v73, v152, v73
	s_waitcnt lgkmcnt(11)
	v_mul_f32_e32 v152, v109, v63
	v_fmac_f32_e32 v152, v108, v62
	v_fmac_f32_e32 v152, v110, v60
	v_fmac_f32_e32 v152, v111, v61
	ds_read_b128 v[108:111], v70 offset:28784
	v_add_f32_e32 v74, 0, v152
	s_waitcnt lgkmcnt(11)
	v_mul_f32_e32 v152, v113, v55
	v_fmac_f32_e32 v152, v112, v54
	v_fmac_f32_e32 v152, v114, v52
	v_fmac_f32_e32 v152, v115, v53
	ds_read_b128 v[112:115], v70 offset:29808
	v_add_f32_e32 v74, v152, v74
	s_waitcnt lgkmcnt(11)
	v_mul_f32_e32 v152, v117, v59
	v_fmac_f32_e32 v152, v116, v58
	v_fmac_f32_e32 v152, v118, v56
	v_fmac_f32_e32 v152, v119, v57
	ds_read_b128 v[116:119], v70 offset:30832
	v_add_f32_e32 v74, v152, v74
	s_waitcnt lgkmcnt(11)
	v_mul_f32_e32 v152, v121, v51
	v_fmac_f32_e32 v152, v120, v50
	v_fmac_f32_e32 v152, v122, v48
	v_fmac_f32_e32 v152, v123, v49
	ds_read_b128 v[120:123], v70 offset:31856
	v_add_f32_e32 v74, v152, v74
	s_waitcnt lgkmcnt(11)
	v_mul_f32_e32 v152, v125, v63
	v_fmac_f32_e32 v152, v124, v62
	v_fmac_f32_e32 v152, v126, v60
	v_fmac_f32_e32 v152, v127, v61
	ds_read_b128 v[124:127], v70 offset:32896
	v_add_f32_e32 v75, 0, v152
	s_waitcnt lgkmcnt(11)
	v_mul_f32_e32 v152, v129, v55
	v_fmac_f32_e32 v152, v128, v54
	v_fmac_f32_e32 v152, v130, v52
	v_fmac_f32_e32 v152, v131, v53
	ds_read_b128 v[128:131], v70 offset:33920
	v_add_f32_e32 v75, v152, v75
	s_waitcnt lgkmcnt(11)
	v_mul_f32_e32 v152, v133, v59
	v_fmac_f32_e32 v152, v132, v58
	v_fmac_f32_e32 v152, v134, v56
	v_fmac_f32_e32 v152, v135, v57
	ds_read_b128 v[132:135], v70 offset:34944
	v_add_f32_e32 v75, v152, v75
	s_waitcnt lgkmcnt(11)
	v_mul_f32_e32 v152, v137, v51
	v_fmac_f32_e32 v152, v136, v50
	v_fmac_f32_e32 v152, v138, v48
	v_fmac_f32_e32 v152, v139, v49
	ds_read_b128 v[136:139], v70 offset:35968
	v_add_f32_e32 v75, v152, v75
	s_waitcnt lgkmcnt(11)
	v_mul_f32_e32 v152, v93, v63
	v_fmac_f32_e32 v152, v92, v62
	v_fmac_f32_e32 v152, v94, v60
	v_fmac_f32_e32 v152, v95, v61
	ds_read_b128 v[92:95], v70 offset:37008
	v_add_f32_e32 v76, 0, v152
	s_waitcnt lgkmcnt(11)
	v_mul_f32_e32 v152, v97, v55
	v_fmac_f32_e32 v152, v96, v54
	v_fmac_f32_e32 v152, v98, v52
	v_fmac_f32_e32 v152, v99, v53
	ds_read_b128 v[96:99], v70 offset:38032
	v_add_f32_e32 v76, v152, v76
	s_waitcnt lgkmcnt(11)
; #define LAS __attribute__((address_space(3)))
; __device__ void phase_ln1_router(const Params& p, int l, LAS unsigned char* lds) {
;     ...
;         float a16[16];
; #pragma unroll
;         for (int e = 0; e < 16; ++e) { float a = 0.f;
; #pragma unroll
;             for (int j = 0; j < 4; ++j) { const f32x4 w = *(const LAS f32x4*)(rw_s + e * RWP + lane * 4 + 256 * j); a += v[j][0] * w[0] + v[j][1] * w[1] + v[j][2] * w[2] + v[j][3] * w[3]; }
;             a16[e] = a; }
	v_mul_f32_e32 v152, v101, v59
	v_fmac_f32_e32 v152, v100, v58
	v_fmac_f32_e32 v152, v102, v56
	v_fmac_f32_e32 v152, v103, v57
	ds_read_b128 v[100:103], v70 offset:39056
	v_add_f32_e32 v76, v152, v76
	s_waitcnt lgkmcnt(11)
	v_mul_f32_e32 v152, v105, v51
	v_fmac_f32_e32 v152, v104, v50
	v_fmac_f32_e32 v152, v106, v48
	v_fmac_f32_e32 v152, v107, v49
	ds_read_b128 v[104:107], v70 offset:40080
	v_add_f32_e32 v76, v152, v76
	s_waitcnt lgkmcnt(11)
	v_mul_f32_e32 v152, v109, v63
	v_fmac_f32_e32 v152, v108, v62
	v_fmac_f32_e32 v152, v110, v60
	v_fmac_f32_e32 v152, v111, v61
	ds_read_b128 v[108:111], v70 offset:41120
	v_add_f32_e32 v77, 0, v152
	s_waitcnt lgkmcnt(11)
	v_mul_f32_e32 v152, v113, v55
	v_fmac_f32_e32 v152, v112, v54
	v_fmac_f32_e32 v152, v114, v52
	v_fmac_f32_e32 v152, v115, v53
	ds_read_b128 v[112:115], v70 offset:42144
	v_add_f32_e32 v77, v152, v77
	s_waitcnt lgkmcnt(11)
	v_mul_f32_e32 v152, v117, v59
	v_fmac_f32_e32 v152, v116, v58
	v_fmac_f32_e32 v152, v118, v56
	v_fmac_f32_e32 v152, v119, v57
	ds_read_b128 v[116:119], v70 offset:43168
	v_add_f32_e32 v77, v152, v77
	s_waitcnt lgkmcnt(11)
	v_mul_f32_e32 v152, v121, v51
	v_fmac_f32_e32 v152, v120, v50
	v_fmac_f32_e32 v152, v122, v48
	v_fmac_f32_e32 v152, v123, v49
	ds_read_b128 v[120:123], v70 offset:44192
	v_add_f32_e32 v77, v152, v77
	s_waitcnt lgkmcnt(11)
	v_mul_f32_e32 v152, v125, v63
	v_fmac_f32_e32 v152, v124, v62
	v_fmac_f32_e32 v152, v126, v60
	v_fmac_f32_e32 v152, v127, v61
	ds_read_b128 v[124:127], v70 offset:45232
	v_add_f32_e32 v78, 0, v152
	s_waitcnt lgkmcnt(11)
	v_mul_f32_e32 v152, v129, v55
	v_fmac_f32_e32 v152, v128, v54
	v_fmac_f32_e32 v152, v130, v52
	v_fmac_f32_e32 v152, v131, v53
	ds_read_b128 v[128:131], v70 offset:46256
	v_add_f32_e32 v78, v152, v78
	s_waitcnt lgkmcnt(11)
	v_mul_f32_e32 v152, v133, v59
	v_fmac_f32_e32 v152, v132, v58
	v_fmac_f32_e32 v152, v134, v56
	v_fmac_f32_e32 v152, v135, v57
	ds_read_b128 v[132:135], v70 offset:47280
	v_add_f32_e32 v78, v152, v78
	s_waitcnt lgkmcnt(11)
	v_mul_f32_e32 v152, v137, v51
	v_fmac_f32_e32 v152, v136, v50
	v_fmac_f32_e32 v152, v138, v48
	v_fmac_f32_e32 v152, v139, v49
	ds_read_b128 v[136:139], v70 offset:48304
	v_add_f32_e32 v78, v152, v78
	s_waitcnt lgkmcnt(11)
	v_mul_f32_e32 v152, v93, v63
	v_fmac_f32_e32 v152, v92, v62
	v_fmac_f32_e32 v152, v94, v60
	v_fmac_f32_e32 v152, v95, v61
	ds_read_b128 v[92:95], v70 offset:49344
	v_add_f32_e32 v79, 0, v152
	s_waitcnt lgkmcnt(11)
	v_mul_f32_e32 v152, v97, v55
	v_fmac_f32_e32 v152, v96, v54
	v_fmac_f32_e32 v152, v98, v52
	v_fmac_f32_e32 v152, v99, v53
	ds_read_b128 v[96:99], v70 offset:50368
	v_add_f32_e32 v79, v152, v79
	s_waitcnt lgkmcnt(11)
	v_mul_f32_e32 v152, v101, v59
	v_fmac_f32_e32 v152, v100, v58
	v_fmac_f32_e32 v152, v102, v56
	v_fmac_f32_e32 v152, v103, v57
	ds_read_b128 v[100:103], v70 offset:51392
	v_add_f32_e32 v79, v152, v79
	s_waitcnt lgkmcnt(11)
	v_mul_f32_e32 v152, v105, v51
	v_fmac_f32_e32 v152, v104, v50
	v_fmac_f32_e32 v152, v106, v48
	v_fmac_f32_e32 v152, v107, v49
	ds_read_b128 v[104:107], v70 offset:52416
	v_add_f32_e32 v79, v152, v79
	s_waitcnt lgkmcnt(11)
	v_mul_f32_e32 v152, v109, v63
	v_fmac_f32_e32 v152, v108, v62
	v_fmac_f32_e32 v152, v110, v60
	v_fmac_f32_e32 v152, v111, v61
	ds_read_b128 v[108:111], v70 offset:53456
	v_add_f32_e32 v80, 0, v152
	s_waitcnt lgkmcnt(11)
	v_mul_f32_e32 v152, v113, v55
	v_fmac_f32_e32 v152, v112, v54
	v_fmac_f32_e32 v152, v114, v52
	v_fmac_f32_e32 v152, v115, v53
	ds_read_b128 v[112:115], v70 offset:54480
	v_add_f32_e32 v80, v152, v80
	s_waitcnt lgkmcnt(11)
	v_mul_f32_e32 v152, v117, v59
	v_fmac_f32_e32 v152, v116, v58
	v_fmac_f32_e32 v152, v118, v56
	v_fmac_f32_e32 v152, v119, v57
	ds_read_b128 v[116:119], v70 offset:55504
	v_add_f32_e32 v80, v152, v80
	s_waitcnt lgkmcnt(11)
	v_mul_f32_e32 v152, v121, v51
	v_fmac_f32_e32 v152, v120, v50
	v_fmac_f32_e32 v152, v122, v48
	v_fmac_f32_e32 v152, v123, v49
	ds_read_b128 v[120:123], v70 offset:56528
	v_add_f32_e32 v80, v152, v80
	s_waitcnt lgkmcnt(11)
	v_mul_f32_e32 v152, v125, v63
	v_fmac_f32_e32 v152, v124, v62
	v_fmac_f32_e32 v152, v126, v60
	v_fmac_f32_e32 v152, v127, v61
	ds_read_b128 v[124:127], v70 offset:57568
	v_add_f32_e32 v81, 0, v152
	s_waitcnt lgkmcnt(11)
	v_mul_f32_e32 v152, v129, v55
	v_fmac_f32_e32 v152, v128, v54
	v_fmac_f32_e32 v152, v130, v52
	v_fmac_f32_e32 v152, v131, v53
	ds_read_b128 v[128:131], v70 offset:58592
	v_add_f32_e32 v81, v152, v81
	s_waitcnt lgkmcnt(11)
	v_mul_f32_e32 v152, v133, v59
	v_fmac_f32_e32 v152, v132, v58
	v_fmac_f32_e32 v152, v134, v56
	v_fmac_f32_e32 v152, v135, v57
	ds_read_b128 v[132:135], v70 offset:59616
	v_add_f32_e32 v81, v152, v81
	s_waitcnt lgkmcnt(11)
	v_mul_f32_e32 v152, v137, v51
	v_fmac_f32_e32 v152, v136, v50
	v_fmac_f32_e32 v152, v138, v48
	v_fmac_f32_e32 v152, v139, v49
	ds_read_b128 v[136:139], v70 offset:60640
	v_add_f32_e32 v81, v152, v81
	s_waitcnt lgkmcnt(11)
	v_mul_f32_e32 v152, v93, v63
	v_fmac_f32_e32 v152, v92, v62
	v_fmac_f32_e32 v152, v94, v60
	v_fmac_f32_e32 v152, v95, v61
	ds_read_b128 v[92:95], v70 offset:61680
	v_add_f32_e32 v82, 0, v152
	s_waitcnt lgkmcnt(11)
	v_mul_f32_e32 v152, v97, v55
	v_fmac_f32_e32 v152, v96, v54
	v_fmac_f32_e32 v152, v98, v52
	v_fmac_f32_e32 v152, v99, v53
	ds_read_b128 v[96:99], v70 offset:62704
	v_add_f32_e32 v82, v152, v82
	s_waitcnt lgkmcnt(11)
	v_mul_f32_e32 v152, v101, v59
	v_fmac_f32_e32 v152, v100, v58
	v_fmac_f32_e32 v152, v102, v56
	v_fmac_f32_e32 v152, v103, v57
	ds_read_b128 v[100:103], v70 offset:63728
	v_add_f32_e32 v82, v152, v82
	s_waitcnt lgkmcnt(11)
; #define LAS __attribute__((address_space(3)))
; __device__ void phase_ln1_router(const Params& p, int l, LAS unsigned char* lds) {
;     ...
;         for (int e = 0; e < 16; ++e) { float a = 0.f;
; #pragma unroll
;             for (int j = 0; j < 4; ++j) { const f32x4 w = *(const LAS f32x4*)(rw_s + e * RWP + lane * 4 + 256 * j); a += v[j][0] * w[0] + v[j][1] * w[1] + v[j][2] * w[2] + v[j][3] * w[3]; }
;             a16[e] = a; }
;         float b8[8], c4[4], d2[2];
;         { const bool hi = (lane & 32) != 0;
; #pragma unroll
;           for (int i = 0; i < 8; ++i) { const float keep = hi ? a16[8 + i] : a16[i], send = hi ? a16[i] : a16[8 + i]; b8[i] = keep + __shfl_xor(send, 32); } }
;         { const bool hi = (lane & 16) != 0;
; #pragma unroll
;           for (int i = 0; i < 4; ++i) { const float keep = hi ? b8[4 + i] : b8[i], send = hi ? b8[i] : b8[4 + i]; c4[i] = keep + __shfl_xor(send, 16); } }
;         { const bool hi = (lane & 8) != 0;
; #pragma unroll
;           for (int i = 0; i < 2; ++i) { const float keep = hi ? c4[2 + i] : c4[i], send = hi ? c4[i] : c4[2 + i]; d2[i] = keep + __shfl_xor(send, 8); } }
;         float lgt; { const bool hi = (lane & 4) != 0; const float keep = hi ? d2[1] : d2[0], send = hi ? d2[0] : d2[1]; lgt = keep + __shfl_xor(send, 4); }
;         lgt += __shfl_xor(lgt, 2); lgt += __shfl_xor(lgt, 1);
;         float mx = lgt;
;         mx = fmaxf(mx, __shfl_xor(mx, 4)); mx = fmaxf(mx, __shfl_xor(mx, 8)); mx = fmaxf(mx, __shfl_xor(mx, 16)); mx = fmaxf(mx, __shfl_xor(mx, 32));
;         const float ex = expf(lgt - mx);
;         float den = ex; den += __shfl_xor(den, 4); den += __shfl_xor(den, 8); den += __shfl_xor(den, 16); den += __shfl_xor(den, 32);
;         const int eidx = ((lane >> 5) & 1) * 8 + ((lane >> 4) & 1) * 4 + ((lane >> 3) & 1) * 2 + ((lane >> 2) & 1);
;         if ((lane & 3) == 0) AFF[(size_t)eidx * SEQ + row] = ex / den;
	v_mul_f32_e32 v152, v105, v51
	v_fmac_f32_e32 v152, v104, v50
	v_fmac_f32_e32 v152, v106, v48
	v_fmac_f32_e32 v152, v107, v49
	ds_read_b128 v[104:107], v70 offset:64752
	v_add_f32_e32 v82, v152, v82
	s_waitcnt lgkmcnt(11)
	v_mul_f32_e32 v152, v109, v63
	v_fmac_f32_e32 v152, v108, v62
	v_fmac_f32_e32 v152, v110, v60
	v_fmac_f32_e32 v152, v111, v61
	v_add_f32_e32 v83, 0, v152
	s_waitcnt lgkmcnt(10)
	v_mul_f32_e32 v152, v113, v55
	v_fmac_f32_e32 v152, v112, v54
	v_fmac_f32_e32 v152, v114, v52
	v_fmac_f32_e32 v152, v115, v53
	v_add_f32_e32 v83, v152, v83
	s_waitcnt lgkmcnt(9)
	v_mul_f32_e32 v152, v117, v59
	v_fmac_f32_e32 v152, v116, v58
	v_fmac_f32_e32 v152, v118, v56
	v_fmac_f32_e32 v152, v119, v57
	v_add_f32_e32 v83, v152, v83
	s_waitcnt lgkmcnt(8)
	v_mul_f32_e32 v152, v121, v51
	v_fmac_f32_e32 v152, v120, v50
	v_fmac_f32_e32 v152, v122, v48
	v_fmac_f32_e32 v152, v123, v49
	v_add_f32_e32 v83, v152, v83
	s_waitcnt lgkmcnt(7)
	v_mul_f32_e32 v152, v125, v63
	v_fmac_f32_e32 v152, v124, v62
	v_fmac_f32_e32 v152, v126, v60
	v_fmac_f32_e32 v152, v127, v61
	v_add_f32_e32 v88, 0, v152
	s_waitcnt lgkmcnt(6)
	v_mul_f32_e32 v152, v129, v55
	v_fmac_f32_e32 v152, v128, v54
	v_fmac_f32_e32 v152, v130, v52
	v_fmac_f32_e32 v152, v131, v53
	v_add_f32_e32 v88, v152, v88
	s_waitcnt lgkmcnt(5)
	v_mul_f32_e32 v152, v133, v59
	v_fmac_f32_e32 v152, v132, v58
	v_fmac_f32_e32 v152, v134, v56
	v_fmac_f32_e32 v152, v135, v57
	v_add_f32_e32 v88, v152, v88
	s_waitcnt lgkmcnt(4)
	v_mul_f32_e32 v152, v137, v51
	v_fmac_f32_e32 v152, v136, v50
	v_fmac_f32_e32 v152, v138, v48
	v_fmac_f32_e32 v152, v139, v49
	v_add_f32_e32 v88, v152, v88
	s_waitcnt lgkmcnt(3)
	v_mul_f32_e32 v152, v93, v63
	v_fmac_f32_e32 v152, v92, v62
	v_fmac_f32_e32 v152, v94, v60
	v_fmac_f32_e32 v152, v95, v61
	v_add_f32_e32 v153, 0, v152
	s_waitcnt lgkmcnt(2)
	v_mul_f32_e32 v152, v97, v55
	v_fmac_f32_e32 v152, v96, v54
	v_fmac_f32_e32 v152, v98, v52
	v_fmac_f32_e32 v152, v99, v53
	v_add_f32_e32 v153, v152, v153
	s_waitcnt lgkmcnt(1)
	v_mul_f32_e32 v152, v101, v59
	v_fmac_f32_e32 v152, v100, v58
	v_fmac_f32_e32 v152, v102, v56
	v_fmac_f32_e32 v152, v103, v57
	v_add_f32_e32 v153, v152, v153
	s_waitcnt lgkmcnt(0)
	v_mul_f32_e32 v152, v105, v51
	v_fmac_f32_e32 v152, v104, v50
	v_fmac_f32_e32 v152, v106, v48
	v_fmac_f32_e32 v152, v107, v49
	v_add_f32_e32 v153, v152, v153
	v_mov_b32_e32 v48, v153
	s_nop 1
	v_permlane32_swap_b32_e32 v33, v78
	v_permlane32_swap_b32_e32 v71, v79
	v_permlane32_swap_b32_e32 v72, v80
	v_permlane32_swap_b32_e32 v73, v81
	v_permlane32_swap_b32_e32 v74, v82
	v_permlane32_swap_b32_e32 v75, v83
	v_permlane32_swap_b32_e32 v76, v88
	v_permlane32_swap_b32_e32 v77, v48
	v_add_f32_e32 v33, v33, v78
	v_add_f32_e32 v49, v71, v79
	v_add_f32_e32 v50, v72, v80
	v_add_f32_e32 v51, v73, v81
	v_add_f32_e32 v52, v74, v82
	v_add_f32_e32 v53, v75, v83
	v_add_f32_e32 v54, v76, v88
	v_add_f32_e32 v48, v77, v48
	s_nop 1
	v_permlane16_swap_b32_e32 v33, v52
	v_permlane16_swap_b32_e32 v49, v53
	v_permlane16_swap_b32_e32 v50, v54
	v_permlane16_swap_b32_e32 v51, v48
	v_add_f32_e32 v33, v33, v52
	v_add_f32_e32 v49, v49, v53
	v_add_f32_e32 v50, v50, v54
	v_add_f32_e32 v48, v51, v48
	v_cndmask_b32_e64 v51, v50, v33, s[8:9]
	v_cndmask_b32_e64 v33, v33, v50, s[8:9]
	v_cndmask_b32_e64 v50, v48, v49, s[8:9]
	v_cndmask_b32_e64 v48, v49, v48, s[8:9]
	s_nop 1
	v_add_f32_dpp v33, v33, v51 row_ror:8 row_mask:0xf bank_mask:0xf
	v_add_f32_dpp v48, v48, v50 row_ror:8 row_mask:0xf bank_mask:0xf
	v_cndmask_b32_e64 v49, v48, v33, s[10:11]
	v_cndmask_b32_e64 v33, v33, v48, s[10:11]
	s_nop 1
	v_mov_b32_dpp v55, v33 row_ror:4 row_mask:0xf bank_mask:0xa
	v_mov_b32_dpp v55, v33 row_ror:12 row_mask:0xf bank_mask:0x5
	v_add_f32_e32 v33, v49, v55
	s_waitcnt lgkmcnt(0)
	s_nop 1
	v_add_f32_dpp v33, v33, v33 quad_perm:[2,3,0,1] row_mask:0xf bank_mask:0xf
	s_waitcnt lgkmcnt(0)
	s_nop 1
	v_add_f32_dpp v33, v33, v33 quad_perm:[1,0,3,2] row_mask:0xf bank_mask:0xf
	s_nop 1
	v_mov_b32_dpp v48, v33 row_ror:4 row_mask:0xf bank_mask:0xa
	v_mov_b32_dpp v48, v33 row_ror:12 row_mask:0xf bank_mask:0x5
	v_max_f32_e32 v48, v33, v48
	s_waitcnt lgkmcnt(0)
	s_nop 1
	v_max_f32_dpp v48, v48, v48 row_ror:8 row_mask:0xf bank_mask:0xf
	v_mov_b32_e32 v49, v48
	s_waitcnt lgkmcnt(0)
	s_nop 1
	v_permlane16_swap_b32_e32 v49, v48
	v_max_f32_e32 v48, v48, v49
	v_mov_b32_e32 v49, v48
	s_waitcnt lgkmcnt(0)
	s_nop 1
	v_permlane32_swap_b32_e32 v49, v48
	v_max_f32_e32 v48, v48, v49
	v_sub_f32_e32 v33, v33, v48
	v_mul_f32_e32 v48, 0x3fb8aa3b, v33
	v_fma_f32 v49, v33, s20, -v48
	v_rndne_f32_e32 v50, v48
	v_fmac_f32_e32 v49, 0x32a5705f, v33
	v_sub_f32_e32 v48, v48, v50
	v_add_f32_e32 v48, v48, v49
	v_exp_f32_e32 v48, v48
	v_cvt_i32_f32_e32 v49, v50
	s_mov_b32 s20, 0xc2ce8ed0
	v_cmp_ngt_f32_e32 vcc, s20, v33
	s_mov_b32 s20, 0x42b17218
	v_ldexp_f32 v48, v48, v49
	v_cndmask_b32_e32 v48, 0, v48, vcc
	v_cmp_nlt_f32_e32 vcc, s20, v33
	v_mov_b32_e32 v33, 0x7f800000
	s_nop 0
	v_cndmask_b32_e32 v33, v33, v48, vcc
	s_nop 1
	v_mov_b32_dpp v48, v33 row_ror:4 row_mask:0xf bank_mask:0xa
	v_mov_b32_dpp v48, v33 row_ror:12 row_mask:0xf bank_mask:0x5
	v_add_f32_e32 v48, v33, v48
	s_waitcnt lgkmcnt(0)
	s_nop 1
	v_add_f32_dpp v48, v48, v48 row_ror:8 row_mask:0xf bank_mask:0xf
	v_mov_b32_e32 v49, v48
	s_waitcnt lgkmcnt(0)
	s_nop 1
	v_permlane16_swap_b32_e32 v49, v48
	v_add_f32_e32 v48, v48, v49
	v_mov_b32_e32 v49, v48
	s_nop 1
	v_permlane32_swap_b32_e32 v49, v48
	v_add_f32_e32 v48, v48, v49
	s_and_saveexec_b64 s[20:21], s[12:13]
	s_cbranch_execz .LBB0_313
	v_div_scale_f32 v49, s[22:23], v48, v48, v33
	v_rcp_f32_e32 v50, v49
	v_div_scale_f32 v51, vcc, v33, v48, v33
	v_fma_f32 v52, -v49, v50, 1.0
	v_fmac_f32_e32 v50, v52, v50
	v_mul_f32_e32 v52, v51, v50
	v_fma_f32 v53, -v49, v52, v51
	v_fmac_f32_e32 v52, v53, v50
	v_fma_f32 v49, -v49, v52, v51
	v_div_fmas_f32 v49, v49, v50, v52
	v_div_fixup_f32 v33, v49, v48, v33
	v_lshl_add_u64 v[48:49], s[86:87], 0, v[38:39]
	global_store_dword v[48:49], v33, off
	s_branch .LBB0_313
